# P0 RMSNorm(x): XN stores with nt (streaming) policy, on top of combined stack
# baseline (speedup 1.0000x reference)
; #define GAS __attribute__((address_space(1)))
; __device__ __forceinline__ void rms_rows4_to_bf16(const float* xrow, const float* g, bf16* orow, int lane) {
;     const GAS f32x4* xr = (const GAS f32x4*)xrow + lane; const GAS f32x4* gr = (const GAS f32x4*)g + lane;
;     f32x4 v[4][4]; float s[4] = {0.f, 0.f, 0.f, 0.f};
; #pragma unroll
;     for (int r = 0; r < 4; ++r)
; #pragma unroll
;         for (int j = 0; j < 4; ++j) v[r][j] = xr[r * (D / 4) + 64 * j];
; #pragma unroll
;     for (int r = 0; r < 4; ++r)
; #pragma unroll
;         for (int j = 0; j < 4; ++j) s[r] += (v[r][j].x * v[r][j].x + v[r][j].y * v[r][j].y) + (v[r][j].z * v[r][j].z + v[r][j].w * v[r][j].w);
.LBB0_59:
	global_load_dwordx4 v[14:17], v[76:77], off
	global_load_dwordx4 v[10:13], v[76:77], off offset:1024
	global_load_dwordx4 v[6:9], v[76:77], off offset:2048
	global_load_dwordx4 v[2:5], v[76:77], off offset:3072
	v_add_co_u32_e32 v22, vcc, 0x1000, v76
	global_load_dwordx4 v[18:21], v[74:75], off
	s_nop 0
	v_addc_co_u32_e32 v23, vcc, 0, v77, vcc
	v_add_co_u32_e32 v24, vcc, 0x2000, v76
	global_load_dwordx4 v[66:69], v[22:23], off
	global_load_dwordx4 v[62:65], v[22:23], off offset:1024
	global_load_dwordx4 v[58:61], v[22:23], off offset:2048
	global_load_dwordx4 v[54:57], v[22:23], off offset:3072
	v_addc_co_u32_e32 v25, vcc, 0, v77, vcc
	global_load_dwordx4 v[50:53], v[24:25], off
	global_load_dwordx4 v[46:49], v[24:25], off offset:1024
	global_load_dwordx4 v[42:45], v[24:25], off offset:2048
	global_load_dwordx4 v[38:41], v[24:25], off offset:3072
	v_add_co_u32_e32 v88, vcc, 0x3000, v76
	v_add_co_u32_e64 v80, s[4:5], s2, v78
	s_nop 0
	v_addc_co_u32_e32 v89, vcc, 0, v77, vcc
	global_load_dwordx4 v[34:37], v[88:89], off
	global_load_dwordx4 v[30:33], v[88:89], off offset:1024
	global_load_dwordx4 v[26:29], v[88:89], off offset:2048
	global_load_dwordx4 v[22:25], v[88:89], off offset:3072
	v_addc_co_u32_e64 v81, s[4:5], 0, v79, s[4:5]
	s_add_i32 s22, s22, s24
	s_cmp_gt_i32 s22, 0xffff
	v_lshl_add_u64 v[76:77], v[76:77], 0, s[26:27]
	s_waitcnt vmcnt(16)
	v_mul_f32_e32 v88, v15, v15
	v_mul_f32_e32 v89, v17, v17
	s_waitcnt vmcnt(15)
	v_mul_f32_e32 v90, v11, v11
	v_mul_f32_e32 v91, v13, v13
	s_waitcnt vmcnt(14)
	v_mul_f32_e32 v92, v7, v7
	v_mul_f32_e32 v93, v9, v9
	s_waitcnt vmcnt(13)
	v_mul_f32_e32 v94, v3, v3
	v_mul_f32_e32 v95, v5, v5
	v_fmac_f32_e32 v88, v14, v14
	v_fmac_f32_e32 v89, v16, v16
	v_fmac_f32_e32 v90, v10, v10
	v_fmac_f32_e32 v91, v12, v12
	v_fmac_f32_e32 v92, v6, v6
	v_fmac_f32_e32 v93, v8, v8
	v_fmac_f32_e32 v94, v2, v2
	v_fmac_f32_e32 v95, v4, v4
	v_add_f32_e32 v88, v88, v89
	v_add_f32_e32 v89, v90, v91
	v_add_f32_e32 v90, v92, v93
	v_add_f32_e32 v91, v94, v95
	s_waitcnt vmcnt(11)
	v_mul_f32_e32 v92, v67, v67
	v_mul_f32_e32 v93, v69, v69
	s_waitcnt vmcnt(10)
	v_mul_f32_e32 v94, v63, v63
	v_mul_f32_e32 v95, v65, v65
	v_add_f32_e32 v88, v88, v89
	s_waitcnt vmcnt(9)
	v_mul_f32_e32 v96, v59, v59
	v_mul_f32_e32 v97, v61, v61
	v_fmac_f32_e32 v92, v66, v66
	v_fmac_f32_e32 v93, v68, v68
	v_fmac_f32_e32 v94, v62, v62
	v_fmac_f32_e32 v95, v64, v64
	s_waitcnt vmcnt(6)
	v_mul_f32_e32 v101, v47, v47
	v_mul_f32_e32 v102, v49, v49
	v_add_f32_e32 v88, v88, v90
	v_mul_f32_e32 v98, v55, v55
	v_mul_f32_e32 v99, v57, v57
	v_fmac_f32_e32 v96, v58, v58
	v_fmac_f32_e32 v97, v60, v60
	v_mul_f32_e32 v89, v51, v51
	v_mul_f32_e32 v100, v53, v53
	v_add_f32_e32 v90, v92, v93
	v_add_f32_e32 v92, v94, v95
	v_fmac_f32_e32 v101, v46, v46
	v_fmac_f32_e32 v102, v48, v48
	v_add_f32_e32 v88, v88, v91
	v_fmac_f32_e32 v98, v54, v54
	v_fmac_f32_e32 v99, v56, v56
	s_waitcnt vmcnt(5)
	v_mul_f32_e32 v103, v43, v43
	v_mul_f32_e32 v104, v45, v45
	v_add_f32_e32 v93, v96, v97
	v_fmac_f32_e32 v89, v50, v50
	v_fmac_f32_e32 v100, v52, v52
	v_add_f32_e32 v90, v90, v92
	v_add_f32_e32 v91, v101, v102
	ds_bpermute_b32 v101, v82, v88
	s_waitcnt vmcnt(4)
	v_mul_f32_e32 v105, v39, v39
	v_mul_f32_e32 v106, v41, v41
	v_add_f32_e32 v94, v98, v99
	v_fmac_f32_e32 v103, v42, v42
	v_fmac_f32_e32 v104, v44, v44
	s_waitcnt vmcnt(3)
	v_mul_f32_e32 v95, v35, v35
	v_mul_f32_e32 v96, v37, v37
	s_waitcnt vmcnt(2)
	v_mul_f32_e32 v97, v31, v31
	v_mul_f32_e32 v98, v33, v33
	v_add_f32_e32 v89, v89, v100
	v_add_f32_e32 v90, v90, v93
	v_fmac_f32_e32 v105, v38, v38
	v_fmac_f32_e32 v106, v40, v40
	s_waitcnt vmcnt(1)
	v_mul_f32_e32 v99, v27, v27
	v_mul_f32_e32 v107, v29, v29
	v_add_f32_e32 v92, v103, v104
	v_fmac_f32_e32 v95, v34, v34
	v_fmac_f32_e32 v96, v36, v36
	v_fmac_f32_e32 v97, v30, v30
	v_fmac_f32_e32 v98, v32, v32
	v_add_f32_e32 v89, v89, v91
	v_add_f32_e32 v90, v90, v94
	s_waitcnt vmcnt(0)
	v_mul_f32_e32 v108, v23, v23
	v_mul_f32_e32 v109, v25, v25
	v_add_f32_e32 v100, v105, v106
	v_fmac_f32_e32 v99, v26, v26
	v_fmac_f32_e32 v107, v28, v28
	v_add_f32_e32 v91, v95, v96
	v_add_f32_e32 v93, v97, v98
	v_add_f32_e32 v89, v89, v92
	ds_bpermute_b32 v92, v82, v90
	v_fmac_f32_e32 v108, v22, v22
	v_fmac_f32_e32 v109, v24, v24
	v_add_f32_e32 v95, v99, v107
	v_add_f32_e32 v91, v91, v93
	v_add_f32_e32 v89, v89, v100
	v_add_f32_e32 v96, v108, v109
	v_add_f32_e32 v91, v91, v95
	ds_bpermute_b32 v93, v82, v89
	s_waitcnt lgkmcnt(2)
	v_add_f32_e32 v88, v88, v101
	v_add_f32_e32 v91, v91, v96
	ds_bpermute_b32 v95, v83, v88
	ds_bpermute_b32 v94, v82, v91
	s_waitcnt lgkmcnt(3)
	v_add_f32_e32 v90, v90, v92
	ds_bpermute_b32 v92, v83, v90
	s_waitcnt lgkmcnt(3)
	v_add_f32_e32 v89, v89, v93
	ds_bpermute_b32 v93, v83, v89
	s_waitcnt lgkmcnt(3)
	v_add_f32_e32 v88, v88, v95
	s_waitcnt lgkmcnt(2)
	v_add_f32_e32 v91, v91, v94
	ds_bpermute_b32 v94, v84, v88
	s_waitcnt lgkmcnt(2)
	v_add_f32_e32 v90, v90, v92
	ds_bpermute_b32 v92, v84, v90
	s_waitcnt lgkmcnt(2)
	v_add_f32_e32 v89, v89, v93
	ds_bpermute_b32 v93, v84, v89
	s_waitcnt lgkmcnt(2)
	v_add_f32_e32 v88, v88, v94
	ds_bpermute_b32 v94, v85, v88
	s_waitcnt lgkmcnt(2)
	v_add_f32_e32 v90, v90, v92
	ds_bpermute_b32 v92, v85, v90
	s_waitcnt lgkmcnt(2)
	v_add_f32_e32 v89, v89, v93
	ds_bpermute_b32 v93, v85, v89
	s_waitcnt lgkmcnt(2)
	v_add_f32_e32 v88, v88, v94
	ds_bpermute_b32 v94, v86, v88
	s_waitcnt lgkmcnt(2)
	v_add_f32_e32 v90, v90, v92
	ds_bpermute_b32 v92, v86, v90
	s_waitcnt lgkmcnt(2)
	v_add_f32_e32 v89, v89, v93
	ds_bpermute_b32 v93, v86, v89
	s_waitcnt lgkmcnt(2)
	v_add_f32_e32 v88, v88, v94
	ds_bpermute_b32 v94, v87, v88
	s_waitcnt lgkmcnt(2)
; #define GAS __attribute__((address_space(1)))
; __device__ __forceinline__ unsigned f2bf(float f) { unsigned u = __builtin_bit_cast(unsigned, f); return (u + 0x7fffu + ((u >> 16) & 1u)) >> 16; }
; __device__ __forceinline__ unsigned pk2(float lo, float hi) { return f2bf(lo) | (f2bf(hi) << 16); }
; __device__ __forceinline__ void rms_rows4_to_bf16(const float* xrow, const float* g, bf16* orow, int lane) {
;     ...
;     for (int r = 0; r < 4; ++r) { const float rs = 1.f / sqrtf(wave_sum(s[r], lane) * (1.f / D) + RMS_EPS);
;         GAS unsigned long long* o8 = (GAS unsigned long long*)(orow + (size_t)r * D) + lane;
; #pragma unroll
;         for (int j = 0; j < 4; ++j) { const f32x4 gg = gr[64 * j];
;             o8[64 * j] = (unsigned long long)pk2(v[r][j].x * rs * gg.x, v[r][j].y * rs * gg.y) | ((unsigned long long)pk2(v[r][j].z * rs * gg.z, v[r][j].w * rs * gg.w) << 32); } }
	v_add_f32_e32 v90, v90, v92
	ds_bpermute_b32 v92, v87, v90
	s_waitcnt lgkmcnt(2)
	v_add_f32_e32 v89, v89, v93
	ds_bpermute_b32 v93, v87, v89
	s_waitcnt lgkmcnt(2)
	v_add_f32_e32 v88, v88, v94
	v_fmamk_f32 v88, v88, 0x3a800000, v71
	v_mul_f32_e32 v94, 0x4f800000, v88
	v_cmp_gt_f32_e32 vcc, s3, v88
	s_waitcnt lgkmcnt(1)
	v_add_f32_e32 v90, v90, v92
	v_fmamk_f32 v90, v90, 0x3a800000, v71
	v_cndmask_b32_e32 v88, v88, v94, vcc
	v_sqrt_f32_e32 v92, v88
	s_waitcnt lgkmcnt(0)
	v_add_f32_e32 v89, v89, v93
	v_mul_f32_e32 v93, 0x4f800000, v90
	v_cmp_gt_f32_e64 s[4:5], s3, v90
	v_fmamk_f32 v89, v89, 0x3a800000, v71
	v_cmp_gt_f32_e64 s[6:7], s3, v89
	v_cndmask_b32_e64 v90, v90, v93, s[4:5]
	v_mul_f32_e32 v93, 0x4f800000, v89
	v_sqrt_f32_e32 v94, v90
	v_cndmask_b32_e64 v89, v89, v93, s[6:7]
	v_add_u32_e32 v95, -1, v92
	v_sqrt_f32_e32 v93, v89
	v_add_u32_e32 v96, 1, v92
	v_fma_f32 v97, -v95, v92, v88
	v_fma_f32 v98, -v96, v92, v88
	v_cmp_ge_f32_e64 s[8:9], 0, v97
	v_add_u32_e32 v97, 1, v94
	v_add_u32_e32 v99, -1, v93
	v_cndmask_b32_e64 v92, v92, v95, s[8:9]
	v_add_u32_e32 v95, -1, v94
	v_cmp_lt_f32_e64 s[8:9], 0, v98
	v_fma_f32 v98, -v97, v94, v90
	v_add_u32_e32 v100, 1, v93
	v_cndmask_b32_e64 v92, v92, v96, s[8:9]
	v_fma_f32 v96, -v95, v94, v90
	v_cmp_ge_f32_e64 s[8:9], 0, v96
	v_mul_f32_e32 v101, 0x37800000, v92
	v_fma_f32 v96, -v100, v93, v89
	v_cndmask_b32_e64 v94, v94, v95, s[8:9]
	v_cmp_lt_f32_e64 s[8:9], 0, v98
	v_fma_f32 v95, -v99, v93, v89
	v_cndmask_b32_e32 v92, v92, v101, vcc
	v_cndmask_b32_e64 v94, v94, v97, s[8:9]
	v_cmp_ge_f32_e32 vcc, 0, v95
	v_cmp_class_f32_e64 s[8:9], v88, v73
	s_nop 0
	v_cndmask_b32_e32 v93, v93, v99, vcc
	v_cmp_lt_f32_e32 vcc, 0, v96
	v_cndmask_b32_e64 v88, v92, v88, s[8:9]
	v_mul_f32_e32 v92, 0x37800000, v94
	v_cndmask_b32_e32 v93, v93, v100, vcc
	v_div_scale_f32 v95, s[8:9], v88, v88, 1.0
	v_cndmask_b32_e64 v92, v94, v92, s[4:5]
	v_cmp_class_f32_e64 s[4:5], v90, v73
	v_mul_f32_e32 v94, 0x37800000, v93
	v_rcp_f32_e32 v97, v95
	v_cndmask_b32_e64 v90, v92, v90, s[4:5]
	v_cndmask_b32_e64 v92, v93, v94, s[6:7]
	v_cmp_class_f32_e64 s[4:5], v89, v73
	v_div_scale_f32 v93, s[6:7], v90, v90, 1.0
	s_nop 0
	v_cndmask_b32_e64 v89, v92, v89, s[4:5]
	v_rcp_f32_e32 v92, v93
	v_div_scale_f32 v98, s[4:5], v89, v89, 1.0
	v_fma_f32 v101, -v95, v97, 1.0
	v_div_scale_f32 v96, vcc, 1.0, v88, 1.0
	v_rcp_f32_e32 v100, v98
	v_fmac_f32_e32 v97, v101, v97
	v_mul_f32_e32 v101, v96, v97
	v_fma_f32 v102, -v93, v92, 1.0
	v_div_scale_f32 v94, s[6:7], 1.0, v90, 1.0
	v_fma_f32 v103, -v95, v101, v96
	v_fmac_f32_e32 v92, v102, v92
	v_fmac_f32_e32 v101, v103, v97
	v_mul_f32_e32 v103, v94, v92
	v_fma_f32 v102, -v98, v100, 1.0
	v_fma_f32 v95, -v95, v101, v96
	v_fma_f32 v96, -v93, v103, v94
	v_div_scale_f32 v99, s[4:5], 1.0, v89, 1.0
	v_fmac_f32_e32 v100, v102, v100
	v_div_fmas_f32 v95, v95, v97, v101
	v_fmac_f32_e32 v103, v96, v92
	v_mul_f32_e32 v102, v99, v100
	v_div_fixup_f32 v88, v95, v88, 1.0
	v_fma_f32 v93, -v93, v103, v94
	s_mov_b64 vcc, s[6:7]
	v_fma_f32 v96, -v98, v102, v99
	v_mul_f32_e32 v14, v14, v88
	v_mul_f32_e32 v16, v16, v88
	v_mul_f32_e32 v94, v2, v88
	v_div_fmas_f32 v2, v93, v92, v103
	v_fmac_f32_e32 v102, v96, v100
	v_mul_f32_e32 v15, v15, v88
	v_mul_f32_e32 v17, v17, v88
	v_mul_f32_e32 v96, v4, v88
	v_mul_f32_e32 v4, v18, v14
	v_mul_f32_e32 v14, v20, v16
	v_div_fixup_f32 v2, v2, v90, 1.0
	v_mul_f32_e32 v10, v10, v88
	v_mul_f32_e32 v11, v11, v88
	v_mul_f32_e32 v12, v12, v88
	v_mul_f32_e32 v13, v13, v88
	v_mul_f32_e32 v6, v6, v88
	v_mul_f32_e32 v7, v7, v88
	v_mul_f32_e32 v8, v8, v88
	v_mul_f32_e32 v9, v9, v88
	v_mul_f32_e32 v95, v3, v88
	v_mul_f32_e32 v88, v5, v88
	v_fma_f32 v3, -v98, v102, v99
	v_mul_f32_e32 v5, v19, v15
	v_mul_f32_e32 v15, v21, v17
	s_mov_b64 vcc, s[4:5]
	v_mul_f32_e32 v16, v66, v2
	v_mul_f32_e32 v17, v67, v2
	v_mul_f32_e32 v18, v68, v2
	v_mul_f32_e32 v19, v69, v2
	v_mul_f32_e32 v20, v62, v2
	v_mul_f32_e32 v21, v63, v2
	v_mul_f32_e32 v62, v64, v2
	v_mul_f32_e32 v63, v65, v2
	v_mul_f32_e32 v58, v58, v2
	v_mul_f32_e32 v59, v59, v2
	v_mul_f32_e32 v60, v60, v2
	v_mul_f32_e32 v61, v61, v2
	v_mul_f32_e32 v54, v54, v2
	v_mul_f32_e32 v55, v55, v2
	v_mul_f32_e32 v56, v56, v2
	v_mul_f32_e32 v57, v57, v2
	v_bfe_u32 v2, v4, 16, 1
	v_bfe_u32 v65, v14, 16, 1
	v_div_fmas_f32 v3, v3, v100, v102
	v_bfe_u32 v64, v5, 16, 1
	v_bfe_u32 v66, v15, 16, 1
	v_add3_u32 v2, v4, v2, s13
	v_add3_u32 v4, v14, v65, s13
	v_div_fixup_f32 v67, v3, v89, 1.0
	v_add3_u32 v3, v5, v64, s13
	v_add3_u32 v5, v15, v66, s13
	v_lshrrev_b32_e32 v2, 16, v2
	v_lshrrev_b32_e32 v4, 16, v4
	v_and_or_b32 v2, v3, s15, v2
	v_and_or_b32 v3, v5, s15, v4
	global_store_dwordx2 v[78:79], v[2:3], off nt
	global_load_dwordx4 v[2:5], v[74:75], off offset:1024
	v_mul_f32_e32 v14, v50, v67
	v_mul_f32_e32 v50, v52, v67
	v_mul_f32_e32 v15, v51, v67
	v_mul_f32_e32 v51, v53, v67
	v_mul_f32_e32 v46, v46, v67
	v_mul_f32_e32 v47, v47, v67
	s_waitcnt vmcnt(0)
	v_mul_f32_e32 v2, v2, v10
	v_mul_f32_e32 v4, v4, v12
	v_mul_f32_e32 v3, v3, v11
	v_mul_f32_e32 v5, v5, v13
	v_bfe_u32 v10, v2, 16, 1
	v_bfe_u32 v12, v4, 16, 1
	v_bfe_u32 v11, v3, 16, 1
	v_bfe_u32 v13, v5, 16, 1
	v_add3_u32 v2, v2, v10, s13
	v_add3_u32 v4, v4, v12, s13
	v_add3_u32 v3, v3, v11, s13
	v_add3_u32 v5, v5, v13, s13
	v_lshrrev_b32_e32 v2, 16, v2
	v_lshrrev_b32_e32 v4, 16, v4
	v_and_or_b32 v2, v3, s15, v2
	v_and_or_b32 v3, v5, s15, v4
	global_store_dwordx2 v[78:79], v[2:3], off offset:512 nt
	global_load_dwordx4 v[2:5], v[74:75], off offset:2048
	v_mul_f32_e32 v10, v45, v67
	s_waitcnt vmcnt(0)
; #define GAS __attribute__((address_space(1)))
; __device__ __forceinline__ unsigned f2bf(float f) { unsigned u = __builtin_bit_cast(unsigned, f); return (u + 0x7fffu + ((u >> 16) & 1u)) >> 16; }
; __device__ __forceinline__ unsigned pk2(float lo, float hi) { return f2bf(lo) | (f2bf(hi) << 16); }
; __device__ __forceinline__ void rms_rows4_to_bf16(const float* xrow, const float* g, bf16* orow, int lane) {
;     ...
;     for (int r = 0; r < 4; ++r) { const float rs = 1.f / sqrtf(wave_sum(s[r], lane) * (1.f / D) + RMS_EPS);
;         GAS unsigned long long* o8 = (GAS unsigned long long*)(orow + (size_t)r * D) + lane;
; #pragma unroll
;         for (int j = 0; j < 4; ++j) { const f32x4 gg = gr[64 * j];
;             o8[64 * j] = (unsigned long long)pk2(v[r][j].x * rs * gg.x, v[r][j].y * rs * gg.y) | ((unsigned long long)pk2(v[r][j].z * rs * gg.z, v[r][j].w * rs * gg.w) << 32); } }
	v_mul_f32_e32 v2, v2, v6
	v_mul_f32_e32 v4, v4, v8
	v_mul_f32_e32 v3, v3, v7
	v_mul_f32_e32 v5, v5, v9
	v_bfe_u32 v6, v2, 16, 1
	v_bfe_u32 v8, v4, 16, 1
	v_bfe_u32 v7, v3, 16, 1
	v_bfe_u32 v9, v5, 16, 1
	v_add3_u32 v2, v2, v6, s13
	v_add3_u32 v4, v4, v8, s13
	v_add3_u32 v3, v3, v7, s13
	v_add3_u32 v5, v5, v9, s13
	v_lshrrev_b32_e32 v2, 16, v2
	v_lshrrev_b32_e32 v4, 16, v4
	v_and_or_b32 v2, v3, s15, v2
	v_and_or_b32 v3, v5, s15, v4
	global_store_dwordx2 v[78:79], v[2:3], off offset:1024 nt
	global_load_dwordx4 v[2:5], v[74:75], off offset:3072
	s_waitcnt vmcnt(0)
	v_mul_f32_e32 v2, v94, v2
	v_mul_f32_e32 v4, v96, v4
	v_mul_f32_e32 v3, v95, v3
	v_mul_f32_e32 v5, v88, v5
	v_bfe_u32 v6, v2, 16, 1
	v_bfe_u32 v8, v4, 16, 1
	v_bfe_u32 v7, v3, 16, 1
	v_bfe_u32 v9, v5, 16, 1
	v_add3_u32 v2, v2, v6, s13
	v_add3_u32 v4, v4, v8, s13
	v_add3_u32 v3, v3, v7, s13
	v_add3_u32 v5, v5, v9, s13
	v_lshrrev_b32_e32 v2, 16, v2
	v_lshrrev_b32_e32 v4, 16, v4
	v_and_or_b32 v2, v3, s15, v2
	v_and_or_b32 v3, v5, s15, v4
	global_store_dwordx2 v[78:79], v[2:3], off offset:1536 nt
	global_load_dwordx4 v[2:5], v[74:75], off
	s_waitcnt vmcnt(0)
	v_mul_f32_e32 v2, v2, v16
	v_mul_f32_e32 v4, v4, v18
	v_mul_f32_e32 v3, v3, v17
	v_mul_f32_e32 v5, v5, v19
	v_bfe_u32 v6, v2, 16, 1
	v_bfe_u32 v8, v4, 16, 1
	v_bfe_u32 v7, v3, 16, 1
	v_bfe_u32 v9, v5, 16, 1
	v_add3_u32 v2, v2, v6, s13
	v_add3_u32 v4, v4, v8, s13
	v_add3_u32 v3, v3, v7, s13
	v_add3_u32 v5, v5, v9, s13
	v_lshrrev_b32_e32 v2, 16, v2
	v_lshrrev_b32_e32 v4, 16, v4
	v_and_or_b32 v2, v3, s15, v2
	v_and_or_b32 v3, v5, s15, v4
	global_store_dwordx2 v[78:79], v[2:3], off offset:2048 nt
	global_load_dwordx4 v[2:5], v[74:75], off offset:1024
	s_waitcnt vmcnt(0)
	v_mul_f32_e32 v2, v2, v20
	v_mul_f32_e32 v4, v4, v62
	v_mul_f32_e32 v3, v3, v21
	v_mul_f32_e32 v5, v5, v63
	v_bfe_u32 v6, v2, 16, 1
	v_bfe_u32 v8, v4, 16, 1
	v_bfe_u32 v7, v3, 16, 1
	v_bfe_u32 v9, v5, 16, 1
	v_add3_u32 v2, v2, v6, s13
	v_add3_u32 v4, v4, v8, s13
	v_add3_u32 v3, v3, v7, s13
	v_add3_u32 v5, v5, v9, s13
	v_lshrrev_b32_e32 v2, 16, v2
	v_lshrrev_b32_e32 v4, 16, v4
	v_and_or_b32 v2, v3, s15, v2
	v_and_or_b32 v3, v5, s15, v4
	global_store_dwordx2 v[78:79], v[2:3], off offset:2560 nt
	global_load_dwordx4 v[2:5], v[74:75], off offset:2048
	s_waitcnt vmcnt(0)
	v_mul_f32_e32 v2, v2, v58
	v_mul_f32_e32 v4, v4, v60
	v_mul_f32_e32 v3, v3, v59
	v_mul_f32_e32 v5, v5, v61
	v_bfe_u32 v6, v2, 16, 1
	v_bfe_u32 v8, v4, 16, 1
	v_bfe_u32 v7, v3, 16, 1
	v_bfe_u32 v9, v5, 16, 1
	v_add3_u32 v2, v2, v6, s13
	v_add3_u32 v4, v4, v8, s13
	v_add3_u32 v3, v3, v7, s13
	v_add3_u32 v5, v5, v9, s13
	v_lshrrev_b32_e32 v2, 16, v2
	v_lshrrev_b32_e32 v4, 16, v4
	v_and_or_b32 v2, v3, s15, v2
	v_and_or_b32 v3, v5, s15, v4
	global_store_dwordx2 v[78:79], v[2:3], off offset:3072 nt
	global_load_dwordx4 v[2:5], v[74:75], off offset:3072
	s_waitcnt vmcnt(0)
	v_mul_f32_e32 v2, v54, v2
	v_mul_f32_e32 v4, v56, v4
	v_mul_f32_e32 v3, v55, v3
	v_mul_f32_e32 v5, v57, v5
	v_bfe_u32 v6, v2, 16, 1
	v_bfe_u32 v8, v4, 16, 1
	v_bfe_u32 v7, v3, 16, 1
	v_bfe_u32 v9, v5, 16, 1
	v_add3_u32 v2, v2, v6, s13
	v_add3_u32 v4, v4, v8, s13
	v_add3_u32 v3, v3, v7, s13
	v_add3_u32 v5, v5, v9, s13
	v_lshrrev_b32_e32 v2, 16, v2
	v_lshrrev_b32_e32 v4, 16, v4
	v_and_or_b32 v2, v3, s15, v2
	v_and_or_b32 v3, v5, s15, v4
	global_store_dwordx2 v[78:79], v[2:3], off offset:3584 nt
	global_load_dwordx4 v[2:5], v[74:75], off
	v_lshl_add_u64 v[78:79], v[78:79], 0, s[28:29]
	s_waitcnt vmcnt(0)
	v_mul_f32_e32 v2, v2, v14
	v_mul_f32_e32 v4, v4, v50
	v_mul_f32_e32 v3, v3, v15
	v_mul_f32_e32 v5, v5, v51
	v_bfe_u32 v6, v2, 16, 1
	v_bfe_u32 v8, v4, 16, 1
	v_bfe_u32 v7, v3, 16, 1
	v_bfe_u32 v9, v5, 16, 1
	v_add3_u32 v2, v2, v6, s13
	v_add3_u32 v4, v4, v8, s13
	v_add3_u32 v3, v3, v7, s13
	v_add3_u32 v5, v5, v9, s13
	v_lshrrev_b32_e32 v2, 16, v2
	v_lshrrev_b32_e32 v4, 16, v4
	v_and_or_b32 v2, v3, s15, v2
	v_and_or_b32 v3, v5, s15, v4
	global_store_dwordx2 v[80:81], v[2:3], off nt
	global_load_dwordx4 v[2:5], v[74:75], off offset:1024
	v_mul_f32_e32 v6, v48, v67
	v_mul_f32_e32 v7, v49, v67
	s_waitcnt vmcnt(0)
	v_mul_f32_e32 v2, v2, v46
	v_mul_f32_e32 v4, v4, v6
	v_mul_f32_e32 v3, v3, v47
	v_mul_f32_e32 v5, v5, v7
	v_bfe_u32 v6, v2, 16, 1
	v_bfe_u32 v8, v4, 16, 1
	v_bfe_u32 v7, v3, 16, 1
	v_bfe_u32 v9, v5, 16, 1
	v_add3_u32 v2, v2, v6, s13
	v_add3_u32 v4, v4, v8, s13
	v_add3_u32 v3, v3, v7, s13
	v_add3_u32 v5, v5, v9, s13
	v_lshrrev_b32_e32 v2, 16, v2
	v_lshrrev_b32_e32 v4, 16, v4
	v_and_or_b32 v2, v3, s15, v2
	v_and_or_b32 v3, v5, s15, v4
	global_store_dwordx2 v[80:81], v[2:3], off offset:512 nt
	global_load_dwordx4 v[2:5], v[74:75], off offset:2048
	ds_bpermute_b32 v6, v83, v91
	v_mul_f32_e32 v9, v44, v67
	v_mul_f32_e32 v8, v43, v67
	s_waitcnt lgkmcnt(0)
	v_add_f32_e32 v6, v91, v6
	ds_bpermute_b32 v7, v84, v6
	s_waitcnt lgkmcnt(0)
	v_add_f32_e32 v6, v6, v7
	v_mul_f32_e32 v7, v42, v67
	s_waitcnt vmcnt(0)
; #define GAS __attribute__((address_space(1)))
; __device__ __forceinline__ unsigned pk2(float lo, float hi) { return f2bf(lo) | (f2bf(hi) << 16); }
; __device__ __forceinline__ float wave_sum(float v, int lane) {
; #pragma unroll
;     for (int o = 1; o < 64; o <<= 1) v += __builtin_bit_cast(float, __builtin_amdgcn_ds_bpermute((lane ^ o) << 2, __builtin_bit_cast(int, v)));
;     return v;
; __device__ __forceinline__ void rms_rows4_to_bf16(const float* xrow, const float* g, bf16* orow, int lane) {
;     ...
;     for (int r = 0; r < 4; ++r) { const float rs = 1.f / sqrtf(wave_sum(s[r], lane) * (1.f / D) + RMS_EPS);
;         GAS unsigned long long* o8 = (GAS unsigned long long*)(orow + (size_t)r * D) + lane;
; #pragma unroll
;         for (int j = 0; j < 4; ++j) { const f32x4 gg = gr[64 * j];
;             o8[64 * j] = (unsigned long long)pk2(v[r][j].x * rs * gg.x, v[r][j].y * rs * gg.y) | ((unsigned long long)pk2(v[r][j].z * rs * gg.z, v[r][j].w * rs * gg.w) << 32); } }
	v_mul_f32_e32 v2, v2, v7
	v_mul_f32_e32 v4, v4, v9
	v_mul_f32_e32 v3, v3, v8
	v_mul_f32_e32 v5, v5, v10
	v_bfe_u32 v7, v2, 16, 1
	v_bfe_u32 v9, v4, 16, 1
	v_bfe_u32 v8, v3, 16, 1
	v_bfe_u32 v10, v5, 16, 1
	v_add3_u32 v2, v2, v7, s13
	v_add3_u32 v4, v4, v9, s13
	v_add3_u32 v3, v3, v8, s13
	v_add3_u32 v5, v5, v10, s13
	v_lshrrev_b32_e32 v2, 16, v2
	v_lshrrev_b32_e32 v4, 16, v4
	v_and_or_b32 v2, v3, s15, v2
	v_and_or_b32 v3, v5, s15, v4
	global_store_dwordx2 v[80:81], v[2:3], off offset:1024 nt
	global_load_dwordx4 v[2:5], v[74:75], off offset:3072
	ds_bpermute_b32 v7, v85, v6
	v_mul_f32_e32 v9, v40, v67
	v_mul_f32_e32 v8, v39, v67
	v_mul_f32_e32 v10, v41, v67
	s_waitcnt lgkmcnt(0)
	v_add_f32_e32 v6, v6, v7
	ds_bpermute_b32 v7, v86, v6
	s_waitcnt lgkmcnt(0)
	v_add_f32_e32 v6, v6, v7
	ds_bpermute_b32 v7, v87, v6
	s_waitcnt lgkmcnt(0)
	v_add_f32_e32 v6, v6, v7
	v_fmamk_f32 v6, v6, 0x3a800000, v71
	v_mul_f32_e32 v7, 0x4f800000, v6
	v_cmp_gt_f32_e32 vcc, s3, v6
	s_waitcnt vmcnt(0)
	v_mul_f32_e32 v4, v9, v4
	v_cndmask_b32_e32 v6, v6, v7, vcc
	v_mul_f32_e32 v7, v38, v67
	v_mul_f32_e32 v2, v7, v2
	v_mul_f32_e32 v3, v8, v3
	v_mul_f32_e32 v5, v10, v5
	v_bfe_u32 v7, v2, 16, 1
	v_bfe_u32 v9, v4, 16, 1
	v_bfe_u32 v8, v3, 16, 1
	v_bfe_u32 v10, v5, 16, 1
	v_add3_u32 v2, v2, v7, s13
	v_add3_u32 v4, v4, v9, s13
	v_add3_u32 v3, v3, v8, s13
	v_add3_u32 v5, v5, v10, s13
	v_lshrrev_b32_e32 v2, 16, v2
	v_lshrrev_b32_e32 v4, 16, v4
	v_and_or_b32 v2, v3, s15, v2
	v_and_or_b32 v3, v5, s15, v4
	global_store_dwordx2 v[80:81], v[2:3], off offset:1536 nt
	global_load_dwordx4 v[2:5], v[74:75], off
	v_sqrt_f32_e32 v7, v6
	s_nop 0
	v_add_u32_e32 v8, -1, v7
	v_add_u32_e32 v9, 1, v7
	v_fma_f32 v10, -v8, v7, v6
	v_fma_f32 v11, -v9, v7, v6
	v_cmp_ge_f32_e64 s[4:5], 0, v10
	s_nop 1
	v_cndmask_b32_e64 v7, v7, v8, s[4:5]
	v_cmp_lt_f32_e64 s[4:5], 0, v11
	s_nop 1
	v_cndmask_b32_e64 v7, v7, v9, s[4:5]
	v_mul_f32_e32 v8, 0x37800000, v7
	v_cndmask_b32_e32 v7, v7, v8, vcc
	v_cmp_class_f32_e32 vcc, v6, v73
	s_nop 1
	v_cndmask_b32_e32 v6, v7, v6, vcc
	v_div_scale_f32 v7, s[4:5], v6, v6, 1.0
	v_rcp_f32_e32 v9, v7
	v_div_scale_f32 v8, vcc, 1.0, v6, 1.0
	v_fma_f32 v10, -v7, v9, 1.0
	v_fmac_f32_e32 v9, v10, v9
	v_mul_f32_e32 v10, v8, v9
	v_fma_f32 v11, -v7, v10, v8
	v_fmac_f32_e32 v10, v11, v9
	v_fma_f32 v7, -v7, v10, v8
	v_div_fmas_f32 v7, v7, v9, v10
	v_div_fixup_f32 v6, v7, v6, 1.0
	v_mul_f32_e32 v7, v34, v6
	v_mul_f32_e32 v9, v36, v6
	v_mul_f32_e32 v8, v35, v6
	v_mul_f32_e32 v10, v37, v6
	s_waitcnt vmcnt(0)
	v_mul_f32_e32 v2, v2, v7
	v_mul_f32_e32 v4, v4, v9
	v_mul_f32_e32 v3, v3, v8
	v_mul_f32_e32 v5, v5, v10
	v_bfe_u32 v7, v2, 16, 1
	v_bfe_u32 v9, v4, 16, 1
	v_bfe_u32 v8, v3, 16, 1
	v_bfe_u32 v10, v5, 16, 1
	v_add3_u32 v2, v2, v7, s13
	v_add3_u32 v4, v4, v9, s13
	v_add3_u32 v3, v3, v8, s13
	v_add3_u32 v5, v5, v10, s13
	v_lshrrev_b32_e32 v2, 16, v2
	v_lshrrev_b32_e32 v4, 16, v4
	v_and_or_b32 v2, v3, s15, v2
	v_and_or_b32 v3, v5, s15, v4
	global_store_dwordx2 v[80:81], v[2:3], off offset:2048 nt
	global_load_dwordx4 v[2:5], v[74:75], off offset:1024
	v_mul_f32_e32 v7, v30, v6
	v_mul_f32_e32 v9, v32, v6
	v_mul_f32_e32 v8, v31, v6
	v_mul_f32_e32 v10, v33, v6
	s_waitcnt vmcnt(0)
	v_mul_f32_e32 v2, v2, v7
	v_mul_f32_e32 v4, v4, v9
	v_mul_f32_e32 v3, v3, v8
	v_mul_f32_e32 v5, v5, v10
	v_bfe_u32 v7, v2, 16, 1
	v_bfe_u32 v9, v4, 16, 1
	v_bfe_u32 v8, v3, 16, 1
	v_bfe_u32 v10, v5, 16, 1
	v_add3_u32 v2, v2, v7, s13
	v_add3_u32 v4, v4, v9, s13
	v_add3_u32 v3, v3, v8, s13
	v_add3_u32 v5, v5, v10, s13
	v_lshrrev_b32_e32 v2, 16, v2
	v_lshrrev_b32_e32 v4, 16, v4
	v_and_or_b32 v2, v3, s15, v2
	v_and_or_b32 v3, v5, s15, v4
	global_store_dwordx2 v[80:81], v[2:3], off offset:2560 nt
	global_load_dwordx4 v[2:5], v[74:75], off offset:2048
	v_mul_f32_e32 v7, v26, v6
	v_mul_f32_e32 v9, v28, v6
	v_mul_f32_e32 v8, v27, v6
	v_mul_f32_e32 v10, v29, v6
	s_waitcnt vmcnt(0)
	v_mul_f32_e32 v2, v2, v7
	v_mul_f32_e32 v4, v4, v9
	v_mul_f32_e32 v3, v3, v8
	v_mul_f32_e32 v5, v5, v10
	v_bfe_u32 v7, v2, 16, 1
	v_bfe_u32 v9, v4, 16, 1
	v_bfe_u32 v8, v3, 16, 1
	v_bfe_u32 v10, v5, 16, 1
	v_add3_u32 v2, v2, v7, s13
	v_add3_u32 v4, v4, v9, s13
	v_add3_u32 v3, v3, v8, s13
	v_add3_u32 v5, v5, v10, s13
	v_lshrrev_b32_e32 v2, 16, v2
	v_lshrrev_b32_e32 v4, 16, v4
	v_and_or_b32 v2, v3, s15, v2
	v_and_or_b32 v3, v5, s15, v4
	global_store_dwordx2 v[80:81], v[2:3], off offset:3072 nt
	global_load_dwordx4 v[2:5], v[74:75], off offset:3072
	v_mul_f32_e32 v7, v22, v6
	v_mul_f32_e32 v9, v24, v6
	v_mul_f32_e32 v8, v23, v6
	v_mul_f32_e32 v6, v25, v6
	s_waitcnt vmcnt(0)
	v_mul_f32_e32 v2, v7, v2
	v_mul_f32_e32 v4, v9, v4
	v_mul_f32_e32 v3, v8, v3
	v_mul_f32_e32 v5, v6, v5
	v_bfe_u32 v6, v2, 16, 1
	v_bfe_u32 v8, v4, 16, 1
	v_bfe_u32 v7, v3, 16, 1
	v_bfe_u32 v9, v5, 16, 1
	v_add3_u32 v2, v2, v6, s13
	v_add3_u32 v4, v4, v8, s13
	v_add3_u32 v3, v3, v7, s13
	v_add3_u32 v5, v5, v9, s13
	v_lshrrev_b32_e32 v2, 16, v2
	v_lshrrev_b32_e32 v4, 16, v4
	v_and_or_b32 v2, v3, s15, v2
	v_and_or_b32 v3, v5, s15, v4
	global_store_dwordx2 v[80:81], v[2:3], off offset:3584 nt
	s_cbranch_scc0 .LBB0_59
